# byte-placement trial: merge phase code shifted by 32 bytes (M K-loop head at offset 16 of a 64-byte line)
# speedup vs baseline: 1.0006x; 1.0006x over previous
; DI int launder_i(int v) { asm volatile("" : "+v"(v)); return v; }
; #define GRID_BAR() xcd_barrier((unsigned*)(ka.ws + OFF_BAR), xb_xcc_id(), (volatile unsigned*)&xb_words)
; DI void xcd_barrier(unsigned* bar, unsigned x, volatile unsigned* st) {
;   asm volatile("s_waitcnt vmcnt(0)" ::: "memory");
;   __syncthreads();
; __global__ void __launch_bounds__(256, 2) mega_kernel(KArgs ka) {
;     ...
;     { Params p = make_params(ka); phase_merge(p, l, smem, launder_i(tid)); } GRID_BAR();
.Lmg_done:
	s_nop 0
	s_nop 0
	s_nop 0
	s_nop 0
	s_nop 0
	s_nop 0
	s_nop 0
	s_nop 0
	s_waitcnt vmcnt(0) lgkmcnt(0)
